# v017 plus MLA attention units remapped so the 8 q-blocks sharing one (batch,head) K/V run on the same XCD (L2 sharing)
# speedup vs baseline: 1.0037x; 1.0001x over previous
; template <int MODE> ...
;     ...
;     const int tid = opq_tid(), wid = tid >> 6, lane = tid & 63, r32 = lane & 31, hi = lane >> 5;
;     char* V_lds = lds + AOFF_V; char* K_lds = lds + AOFF_K; char* K2_lds = lds + AOFF_K2; char* tbl = lds + AOFF_TBL;
;     float* ws = (float*)(lds + AOFF_WS) + wid * 64; float* li_l = ws; float* al_l = ws + 32;
;     __syncthreads();
;     int rq = 0, rs_row = 0, tcol = 0; unsigned mask0 = 0, mask1 = 0;
;     if constexpr (MODE == 1) {
;         for (int i = tid; i < 15 * 128; i += 512) { const int dr = i >> 7, t = (i & 127) - 63; const int dc = (t < -15 ? -15 : (t > 15 ? 15 : t)) + 15;
;             ((float*)tbl)[i] = rpb_h[dr * 31 + dc] * (1.0f / CF::SCALE); }
;         rq = na_r0 + (wid >> 1); rs_row = rq - 4 < 0 ? 0 : (rq - 4 > 24 ? 24 : rq - 4);
;         const int cq = (wid & 1) * 32 + r32; const int cs = cq - 8 < 0 ? 0 : (cq - 8 > 48 ? 48 : cq - 8);
;         tcol = 63 - cq + 4 * hi;
; #pragma unroll
;         for (int r = 0; r < 16; ++r) { const int ck = crow(r, hi);
;             mask0 |= ((unsigned)(ck - cs) < 16u ? 1u : 0u) << r; mask1 |= ((unsigned)(ck + 32 - cs) < 16u ? 1u : 0u) << r; }
;     }
;     float m_reg = -1e30f, l_reg = 0;
;     f32x16 o[4];
; #pragma unroll
;     for (int d = 0; d < 4; ++d)
; #pragma unroll
;         for (int r = 0; r < 16; ++r) o[d][r] = 0.f;
;     bf16x8 qr[CF::ND0];
;     const bf16_t* Qw = Qb + (long)(wid * 32 + r32) * LDQ + hi * 8;
; #pragma unroll
;     for (int d0 = 0; d0 < CF::ND0; ++d0) qr[d0] = *reinterpret_cast<const bf16x8*>(Qw + d0 * 16);
;     char* Q2_lds = lds + AOFF_Q2 + wid * 4096;
;     const int sr = tid >> 4, sc = (tid & 15) * 8, vst0 = v_st(sr, sc), vst1 = v_st(32 + sr, sc);
;     const int s2r = tid >> 3, s2c = (tid & 7) * 8;
;     const int vb0 = (int)(uintptr_t)V_lds + v_rd_base(lane);
;     struct { bf16x8 vs0, vs1, ks0, ks1, k2; } sr_[SDEPTH];
;     ...
;     f32x16 pA0, pA1; float mnA, alA; bf16x8 pa0, pa1, pa2, pa3;
; __device__ __forceinline__ void phase5(const Params& P, char* lds) {
;     ...
;             const int b = u >> 6, h = (u >> 3) & 7, qb = u & 7;
;             const size_t tok0 = (size_t)b * SEQ;
;             attn_body<0>(q + (tok0 + qb * 256) * 1536 + h * 192, kv + tok0 * 2048 + h * 256, kv + tok0 * 2048 + h * 256 + 128, kr + tok0 * 64,
;                          att + (tok0 + qb * 256) * 2048 + 1024 + h * 128, SEQ / KVBLK, 0, 0, nullptr, lds);
.LBB0_779:
	s_ashr_i32 s22, s39, 6
	s_ashr_i32 s23, s22, 31
	s_lshl_b32 s6, s39, 5
	s_lshl_b64 s[20:21], s[22:23], 11
	s_and_b32 s6, s6, 0x700
	s_or_b32 s20, s20, s6
	s_bfe_u32 s40, s39, 0x30000
	s_mul_i32 s6, s21, 0xc00
	s_mul_hi_u32 s7, s20, 0xc00
	s_lshl_b32 s41, s40, 9
	s_add_i32 s7, s7, s6
	s_mul_i32 s6, s20, 0xc00
	s_add_u32 s6, s0, s6
	s_addc_u32 s7, s1, s7
	s_mul_i32 s8, s40, 0x180
	s_add_u32 s6, s6, s8
	s_addc_u32 s7, s7, 0
	s_lshl_b64 s[8:9], s[22:23], 23
	s_add_u32 s42, s2, s8
	s_addc_u32 s43, s3, s9
	v_mov_b32_e32 v32, v254
	s_add_u32 s42, s42, s41
	s_addc_u32 s43, s43, 0
	v_ashrrev_i32_e32 v20, 4, v32
	v_lshlrev_b32_e32 v33, 3, v32
	s_lshl_b64 s[22:23], s[22:23], 18
	v_and_b32_e32 v0, 0x78, v33
	v_ashrrev_i32_e32 v22, 3, v32
	v_ashrrev_i32_e32 v21, 31, v20
	s_add_u32 s44, s4, s22
	v_lshlrev_b32_e32 v34, 1, v0
	v_lshlrev_b64 v[24:25], 12, v[20:21]
	v_ashrrev_i32_e32 v23, 31, v22
	s_addc_u32 s45, s5, s23
	v_or_b32_e32 v0, v24, v34
	v_mov_b32_e32 v1, v25
	v_lshlrev_b32_e32 v21, 4, v32
	v_lshlrev_b64 v[26:27], 7, v[22:23]
	v_lshl_add_u64 v[12:13], s[42:43], 0, v[0:1]
	v_lshl_add_u64 v[16:17], s[44:45], 0, v[26:27]
	v_and_b32_e32 v28, 0x70, v21
	v_mov_b32_e32 v29, v165
	s_waitcnt vmcnt(0) lgkmcnt(0)
	s_barrier
	global_load_dwordx4 v[0:3], v[12:13], off offset:256
	v_lshl_add_u64 v[4:5], v[12:13], 0, s[12:13]
	v_lshl_add_u64 v[16:17], v[16:17], 0, v[28:29]
	v_ashrrev_i32_e32 v29, 1, v32
	global_load_dwordx4 v[4:7], v[4:5], off offset:256
	v_bfe_u32 v172, v32, 5, 1
	v_and_b32_e32 v166, 0xffffffe0, v29
	v_bfi_b32 v29, s26, v29, v32
	v_mov_b64_e32 v[30:31], s[6:7]
	global_load_dwordx4 v[8:11], v[12:13], off
	v_add_co_u32_e32 v12, vcc, s28, v12
	v_mad_i64_i32 v[30:31], s[6:7], v29, s24, v[30:31]
	v_lshlrev_b32_e32 v164, 4, v172
	v_addc_co_u32_e32 v13, vcc, 0, v13, vcc
	v_lshl_add_u64 v[30:31], v[30:31], 0, v[164:165]
	global_load_dwordx4 v[12:15], v[12:13], off
	v_and_b32_e32 v29, 0xfffff0, v20
	global_load_dwordx4 v[16:19], v[16:17], off
	s_nop 0
	global_load_dwordx4 v[140:143], v[30:31], off
	global_load_dwordx4 v[136:139], v[30:31], off offset:32
	global_load_dwordx4 v[132:135], v[30:31], off offset:64
	global_load_dwordx4 v[128:131], v[30:31], off offset:96
	global_load_dwordx4 v[124:127], v[30:31], off offset:128
	global_load_dwordx4 v[120:123], v[30:31], off offset:160
	global_load_dwordx4 v[116:119], v[30:31], off offset:192
	global_load_dwordx4 v[112:115], v[30:31], off offset:224
	global_load_dwordx4 v[108:111], v[30:31], off offset:256
	global_load_dwordx4 v[104:107], v[30:31], off offset:288
	global_load_dwordx4 v[100:103], v[30:31], off offset:320
	global_load_dwordx4 v[96:99], v[30:31], off offset:352
	v_lshlrev_b32_e32 v30, 1, v20
	v_and_or_b32 v29, v30, 8, v29
	v_lshrrev_b32_e32 v30, 1, v20
	v_lshrrev_b32_e32 v29, 1, v29
	v_bfe_u32 v31, v33, 5, 2
	v_and_b32_e32 v35, 3, v20
	v_or_b32_e32 v29, v29, v31
	v_and_or_b32 v30, v30, 4, v35
	v_lshlrev_b32_e32 v29, 9, v29
	v_lshlrev_b32_e32 v30, 6, v30
	v_and_b32_e32 v35, 48, v34
	v_or3_b32 v186, v29, v30, v35
	v_add_u32_e32 v29, 32, v20
	v_and_b32_e32 v36, 0xfffff0, v29
	v_lshlrev_b32_e32 v37, 1, v29
	v_and_or_b32 v36, v37, 8, v36
	v_lshrrev_b32_e32 v36, 1, v36
	v_or_b32_e32 v31, v36, v31
	v_lshlrev_b32_e32 v31, 9, v31
	v_or3_b32 v188, v31, v30, v35
	v_add_u32_e32 v35, 0, v186
	s_waitcnt vmcnt(0)
	v_lshlrev_b32_e32 v31, 1, v32
	s_cmp_lg_u32 0, -1
	v_and_b32_e32 v31, 32, v31
	s_cselect_b32 s42, 0, 0
	s_add_u32 s22, s22, 0x19902000
	v_and_b32_e32 v30, 0xc0, v21
	s_addc_u32 s23, s23, 0
	v_lshl_add_u64 v[168:169], s[22:23], 0, v[26:27]
	v_and_b32_e32 v23, 0x3fffffc0, v32
	v_lshl_add_u32 v174, v23, 2, s25
	v_and_b32_e32 v23, 63, v32
	v_lshl_add_u64 v[170:171], s[8:9], 0, v[24:25]
	v_and_b32_e32 v173, 31, v32
	v_bitop3_b32 v182, v164, v21, s29 bitop3:0x78
	v_bitop3_b32 v181, v164, v28, 32 bitop3:0x36
	v_bitop3_b32 v180, v164, v28, 64 bitop3:0x36
	v_bitop3_b32 v178, v164, v28, s31 bitop3:0x36
	v_bitop3_b32 v189, v164, v28, s33 bitop3:0x36
	v_bitop3_b32 v187, v164, v28, s34 bitop3:0x36
	v_bitop3_b32 v185, v164, v28, s27 bitop3:0x36
	v_bitop3_b32 v184, v164, v28, s35 bitop3:0x36
	v_cmp_gt_u32_e64 s[6:7], 32, v23
	v_lshlrev_b32_e32 v183, 8, v173
	v_lshlrev_b32_e32 v179, 7, v173
	v_lshl_add_u32 v167, v173, 2, v174
	v_mov_b32_e32 v176, 0xf149f2ca
	v_mov_b32_e32 v193, 0
	s_waitcnt vmcnt(16)
	ds_write_b128 v35, v[0:3]
	v_add_u32_e32 v0, 0, v188
	v_and_b32_e32 v1, 0x70, v32
	v_mov_b32_e32 v2, v165
	s_waitcnt vmcnt(15)
	ds_write_b128 v0, v[4:7]
	v_lshlrev_b32_e32 v0, 8, v20
	v_bitop3_b32 v190, v34, v0, v1 bitop3:0xde
	v_add_u32_e32 v0, 0, v190
	v_mov_b32_e32 v3, v165
	s_waitcnt vmcnt(14)
	ds_write_b128 v0, v[8:11] offset:32768
	v_lshlrev_b32_e32 v0, 8, v29
	v_bitop3_b32 v191, v34, v0, v1 bitop3:0xde
	v_add_u32_e32 v0, 0, v191
	v_lshlrev_b32_e32 v1, 4, v22
	v_bitop3_b32 v1, v21, v1, s29 bitop3:0x28
	v_mov_b32_e32 v4, v165
	v_mov_b32_e32 v5, v165
	v_mov_b32_e32 v6, v165
	s_waitcnt vmcnt(13)
	ds_write_b128 v0, v[12:15] offset:32768
	v_lshlrev_b32_e32 v0, 7, v22
	v_add3_u32 v192, s30, v1, v0
	v_and_or_b32 v0, v33, s36, v31
	v_add3_u32 v175, v30, s42, v0
	v_and_b32_e32 v0, 7, v32
	v_lshl_or_b32 v168, v0, 4, v168
	v_and_b32_e32 v0, 15, v32
	v_lshlrev_b32_e32 v0, 4, v0
	v_mov_b32_e32 v14, v165
	v_mov_b32_e32 v15, v165
	s_waitcnt vmcnt(12)
	ds_write_b128 v192, v[16:19]
	v_or3_b32 v170, v170, s41, v0
	v_mov_b32_e32 v0, v165
	v_mov_b32_e32 v1, v165
	v_mov_b32_e32 v7, v165
	v_mov_b32_e32 v8, v165
	v_mov_b32_e32 v9, v165
	v_mov_b32_e32 v10, v165
	v_mov_b32_e32 v11, v165
	v_mov_b32_e32 v12, v165
	v_mov_b32_e32 v13, v165
	v_mov_b64_e32 v[62:63], v[14:15]
	v_mov_b64_e32 v[46:47], v[14:15]
	v_mov_b64_e32 v[30:31], v[14:15]
	v_mov_b64_e32 v[60:61], v[12:13]
	v_mov_b64_e32 v[58:59], v[10:11]
	v_mov_b64_e32 v[56:57], v[8:9]
	v_mov_b64_e32 v[54:55], v[6:7]
	v_mov_b64_e32 v[52:53], v[4:5]
	v_mov_b64_e32 v[50:51], v[2:3]
	v_mov_b64_e32 v[48:49], v[0:1]
	v_mov_b64_e32 v[44:45], v[12:13]
	v_mov_b64_e32 v[42:43], v[10:11]
	v_mov_b64_e32 v[40:41], v[8:9]
	v_mov_b64_e32 v[38:39], v[6:7]
	v_mov_b64_e32 v[36:37], v[4:5]
	v_mov_b64_e32 v[34:35], v[2:3]
	v_mov_b64_e32 v[32:33], v[0:1]
	v_mov_b64_e32 v[28:29], v[12:13]
	v_mov_b64_e32 v[26:27], v[10:11]
	v_mov_b64_e32 v[24:25], v[8:9]
	v_mov_b64_e32 v[22:23], v[6:7]
	v_mov_b64_e32 v[20:21], v[4:5]
	v_mov_b64_e32 v[18:19], v[2:3]
	v_mov_b64_e32 v[16:17], v[0:1]
	s_mov_b32 s41, 0
	s_waitcnt lgkmcnt(0)
	s_barrier
